# slot routine three items in flight, original conversion schedule (table-driven)
# speedup vs baseline: 1.0078x; 1.0053x over previous
;     ...
;     for (int mi = 0; mi < 7 * DEPTH; ++mi) {
;         if (!((mask >> mi) & 1u)) continue;
;         const int l = mi / 7, kind = mi - 7 * l;
;         const float* W; const float* ks = nullptr; bf16_t* WT; int K, N, rm = 0;
;         if (kind == 0)      { W = a.in[2] + (size_t)l * 2048 * 7680;  K = 2048; N = 7680; WT = (bf16_t*)(ws + WS_WIN + l * SZ_WIN); ks = a.in[1] + l * 2048; rm = 3; }
;         else if (kind == 1) { W = a.in[10] + (size_t)l * 1024 * 2048; K = 1024; N = 2048; WT = (bf16_t*)(ws + WS_WA + l * SZ_WA); }
;         else if (kind == 2) { W = a.in[11] + (size_t)l * 1024 * 2048; K = 1024; N = 2048; WT = (bf16_t*)(ws + WS_WB + l * SZ_WB); }
;         else if (kind == 3) { W = a.in[12] + (size_t)l * 2048 * 2048; K = 2048; N = 2048; WT = (bf16_t*)(ws + WS_WO + l * SZ_WO); }
;         else if (kind == 4) { W = a.in[14] + (size_t)l * 2048 * 5632; K = 2048; N = 5632; WT = (bf16_t*)(ws + WS_WGU + l * SZ_WGU); ks = a.in[13] + l * 2048; rm = 1; }
;         else if (kind == 5) { W = a.in[15] + (size_t)l * 2048 * 5632; K = 2048; N = 5632; WT = (bf16_t*)(ws + WS_WGU + l * SZ_WGU); ks = a.in[13] + l * 2048; rm = 2; }
;         else                { W = a.in[16] + (size_t)l * 5632 * 2048; K = 5632; N = 2048; WT = (bf16_t*)(ws + WS_WD + l * SZ_WD); }
; __global__ void __launch_bounds__(NTHREADS, 2) mk_fwd(Args args) {
;     ...
;                 if (blk >= thr) p0_prologue(args, (blk - thr) * NWAVES + wave, (G - thr) * NWAVES, lane, l == 0 ? 0x0030u : 0x1800u, false, l == 0 ? 0x0010u : 0x0800u, 10, 16); }
.Lsl_in_dispatch:
	s_cmp_eq_u32 s28, 0
	s_cbranch_scc1 .Lsl_in_set0
	s_cmp_eq_u32 s28, 1
	s_cbranch_scc1 .Lsl_in_set1
	s_cmp_eq_u32 s28, 16
	s_cbranch_scc1 .Lsl_in_set16
	s_cmp_eq_u32 s28, 17
	s_cbranch_scc1 .Lsl_in_set17
	s_branch .LBB0_256

;     ...
;         if (kind == 0)      { W = a.in[2] + (size_t)l * 2048 * 7680;  K = 2048; N = 7680; WT = (bf16_t*)(ws + WS_WIN + l * SZ_WIN); ks = a.in[1] + l * 2048; rm = 3; }
;         else if (kind == 1) { W = a.in[10] + (size_t)l * 1024 * 2048; K = 1024; N = 2048; WT = (bf16_t*)(ws + WS_WA + l * SZ_WA); }
;         else if (kind == 2) { W = a.in[11] + (size_t)l * 1024 * 2048; K = 1024; N = 2048; WT = (bf16_t*)(ws + WS_WB + l * SZ_WB); }
;         else if (kind == 3) { W = a.in[12] + (size_t)l * 2048 * 2048; K = 2048; N = 2048; WT = (bf16_t*)(ws + WS_WO + l * SZ_WO); }
;         else if (kind == 4) { W = a.in[14] + (size_t)l * 2048 * 5632; K = 2048; N = 5632; WT = (bf16_t*)(ws + WS_WGU + l * SZ_WGU); ks = a.in[13] + l * 2048; rm = 1; }
;         else if (kind == 5) { W = a.in[15] + (size_t)l * 2048 * 5632; K = 2048; N = 5632; WT = (bf16_t*)(ws + WS_WGU + l * SZ_WGU); ks = a.in[13] + l * 2048; rm = 2; }
;         else                { W = a.in[16] + (size_t)l * 5632 * 2048; K = 5632; N = 2048; WT = (bf16_t*)(ws + WS_WD + l * SZ_WD); }
;         const int nitems = (K >> 6) * (N >> 5);
;         int ilo = 0, ihi = nitems; if ((fmask >> mi) & 1u) { ilo = (nitems * flo) >> 4; ihi = (nitems * fhi) >> 4; }
;         const int cnt = ihi - ilo;
;         int first = (gw - base) % NGW; if (first < 0) first += NGW;
;         for (int it = first; it < cnt; it += NGW) tr_item(W, K, N, WT, ks, rm, ilo + it, lane);
;         base = (base + cnt) % NGW;
.Lsl_in_set1:
	v_readlane_b32 s22, v250, 32
	v_readlane_b32 s23, v250, 33
	v_readlane_b32 s24, v250, 36
	v_readlane_b32 s25, v250, 37
	v_readlane_b32 s26, v250, 28
	v_readlane_b32 s27, v250, 29
	v_mul_u32_u24_e32 v104, 0x2c000, v102
	v_lshl_add_u32 v104, v103, 4, v104
	v_mul_u32_u24_e32 v105, 0x4000, v103
	v_lshl_add_u32 v105, v102, 4, v105
	s_add_u32 s24, s24, 0x5dc0000
	s_addc_u32 s25, s25, 0
	s_mov_b32 s36, 0x5800
	s_mov_b32 s37, 0x160000
	s_movk_i32 s38, 2979
	s_mov_b32 s39, 19
	s_movk_i32 s40, 176
	s_movk_i32 s41, 0x1000
	s_mov_b32 s42, 2
	s_mov_b32 s43, 1
	s_movk_i32 s44, 0
	s_movk_i32 s29, 5632
	s_sub_i32 s4, s2, 64
	s_and_b32 s4, s4, 511
	s_branch .Lsl_in_loop
.Lsl_in_set16:
	v_readlane_b32 s22, v250, 30
	v_readlane_b32 s23, v250, 31
	v_readlane_b32 s24, v250, 36
	v_readlane_b32 s25, v250, 37
	v_readlane_b32 s26, v250, 28
	v_readlane_b32 s27, v250, 29
	v_mul_u32_u24_e32 v104, 0x2c000, v102
	v_lshl_add_u32 v104, v103, 4, v104
	v_mul_u32_u24_e32 v105, 0x4000, v103
	v_lshl_add_u32 v105, v102, 4, v105
	s_add_u32 s22, s22, 0x2c00000
	s_addc_u32 s23, s23, 0
	s_add_u32 s24, s24, 0x89c0000
	s_addc_u32 s25, s25, 0
	s_add_u32 s26, s26, 0x2000
	s_addc_u32 s27, s27, 0
	s_mov_b32 s36, 0x5800
	s_mov_b32 s37, 0x160000
	s_movk_i32 s38, 2979
	s_mov_b32 s39, 19
	s_movk_i32 s40, 176
	s_movk_i32 s41, 0x1000
	s_mov_b32 s42, 1
	s_mov_b32 s43, 1
	s_movk_i32 s44, 3520
	s_movk_i32 s29, 2112
	s_sub_i32 s4, s2, 0
	s_and_b32 s4, s4, 511
	s_branch .Lsl_in_loop
.Lsl_in_set17:
	v_readlane_b32 s22, v250, 32
	v_readlane_b32 s23, v250, 33
	v_readlane_b32 s24, v250, 36
	v_readlane_b32 s25, v250, 37
	v_readlane_b32 s26, v250, 28
	v_readlane_b32 s27, v250, 29
	v_mul_u32_u24_e32 v104, 0x2c000, v102
	v_lshl_add_u32 v104, v103, 4, v104
	v_mul_u32_u24_e32 v105, 0x4000, v103
	v_lshl_add_u32 v105, v102, 4, v105
	s_add_u32 s22, s22, 0x2c00000
	s_addc_u32 s23, s23, 0
	s_add_u32 s24, s24, 0x89c0000
	s_addc_u32 s25, s25, 0
	s_add_u32 s26, s26, 0x2000
	s_addc_u32 s27, s27, 0
	s_mov_b32 s36, 0x5800
	s_mov_b32 s37, 0x160000
	s_movk_i32 s38, 2979
	s_mov_b32 s39, 19
	s_movk_i32 s40, 176
	s_movk_i32 s41, 0x1000
	s_mov_b32 s42, 2
	s_mov_b32 s43, 1
	s_movk_i32 s44, 0
	s_movk_i32 s29, 5632
	s_sub_i32 s4, s2, 64
	s_and_b32 s4, s4, 511
	s_branch .Lsl_in_loop
.Lsl_in_loop:
	s_cmp_ge_u32 s4, s29
	s_cbranch_scc1 .Lsl_in_next
	s_add_i32 s16, s4, s44
	s_mul_i32 s17, s16, s38
	s_lshr_b32 s17, s17, s39
	s_mul_i32 s19, s17, s40
	s_sub_i32 s18, s16, s19
	s_mul_i32 s19, s17, s37
	s_lshl_b32 s20, s18, 7
	s_add_i32 s19, s19, s20
	v_add_u32_e32 v42, s19, v104
	s_cmp_eq_u32 s43, 0
	s_cbranch_scc1 .Lsl_in_nks1
	s_lshl_b32 s19, s17, 8
	v_add_u32_e32 v43, s19, v110
	global_load_dwordx4 v[34:37], v43, s[26:27]
	global_load_dwordx4 v[38:41], v43, s[26:27] offset:16

;     ...
;     for (int mi = 0; mi < 7 * DEPTH; ++mi) {
;         if (!((mask >> mi) & 1u)) continue;
;         const int l = mi / 7, kind = mi - 7 * l;
;         const float* W; const float* ks = nullptr; bf16_t* WT; int K, N, rm = 0;
;         if (kind == 0)      { W = a.in[2] + (size_t)l * 2048 * 7680;  K = 2048; N = 7680; WT = (bf16_t*)(ws + WS_WIN + l * SZ_WIN); ks = a.in[1] + l * 2048; rm = 3; }
;         else if (kind == 1) { W = a.in[10] + (size_t)l * 1024 * 2048; K = 1024; N = 2048; WT = (bf16_t*)(ws + WS_WA + l * SZ_WA); }
;         else if (kind == 2) { W = a.in[11] + (size_t)l * 1024 * 2048; K = 1024; N = 2048; WT = (bf16_t*)(ws + WS_WB + l * SZ_WB); }
;         else if (kind == 3) { W = a.in[12] + (size_t)l * 2048 * 2048; K = 2048; N = 2048; WT = (bf16_t*)(ws + WS_WO + l * SZ_WO); }
;         else if (kind == 4) { W = a.in[14] + (size_t)l * 2048 * 5632; K = 2048; N = 5632; WT = (bf16_t*)(ws + WS_WGU + l * SZ_WGU); ks = a.in[13] + l * 2048; rm = 1; }
;         else if (kind == 5) { W = a.in[15] + (size_t)l * 2048 * 5632; K = 2048; N = 5632; WT = (bf16_t*)(ws + WS_WGU + l * SZ_WGU); ks = a.in[13] + l * 2048; rm = 2; }
;         else                { W = a.in[16] + (size_t)l * 5632 * 2048; K = 5632; N = 2048; WT = (bf16_t*)(ws + WS_WD + l * SZ_WD); }
; __global__ void __launch_bounds__(NTHREADS, 2) mk_fwd(Args args) {
;     ...
;                 if (blk >= thr) p0_prologue(args, (blk - thr) * NWAVES + wave, (G - thr) * NWAVES, lane, l == 0 ? 0x07C0u : 0x2000u, false); }
.Lsl_gu_dispatch:
	s_cmp_eq_u32 s28, 0
	s_cbranch_scc1 .Lsl_gu_set0
	s_cmp_eq_u32 s28, 1
	s_cbranch_scc1 .Lsl_gu_set1
	s_cmp_eq_u32 s28, 2
	s_cbranch_scc1 .Lsl_gu_set2
	s_cmp_eq_u32 s28, 3
	s_cbranch_scc1 .Lsl_gu_set3
	s_cmp_eq_u32 s28, 4
	s_cbranch_scc1 .Lsl_gu_set4
	s_cmp_eq_u32 s28, 16
	s_cbranch_scc1 .Lsl_gu_set16
	s_branch .LBB0_716

;     ...
;         else if (kind == 1) { W = a.in[10] + (size_t)l * 1024 * 2048; K = 1024; N = 2048; WT = (bf16_t*)(ws + WS_WA + l * SZ_WA); }
;         else if (kind == 2) { W = a.in[11] + (size_t)l * 1024 * 2048; K = 1024; N = 2048; WT = (bf16_t*)(ws + WS_WB + l * SZ_WB); }
;         else if (kind == 3) { W = a.in[12] + (size_t)l * 2048 * 2048; K = 2048; N = 2048; WT = (bf16_t*)(ws + WS_WO + l * SZ_WO); }
;         else if (kind == 4) { W = a.in[14] + (size_t)l * 2048 * 5632; K = 2048; N = 5632; WT = (bf16_t*)(ws + WS_WGU + l * SZ_WGU); ks = a.in[13] + l * 2048; rm = 1; }
;         else if (kind == 5) { W = a.in[15] + (size_t)l * 2048 * 5632; K = 2048; N = 5632; WT = (bf16_t*)(ws + WS_WGU + l * SZ_WGU); ks = a.in[13] + l * 2048; rm = 2; }
;         else                { W = a.in[16] + (size_t)l * 5632 * 2048; K = 5632; N = 2048; WT = (bf16_t*)(ws + WS_WD + l * SZ_WD); }
.Lsl_gu_set2:
	v_readlane_b32 s22, v250, 22
	v_readlane_b32 s23, v250, 23
	v_readlane_b32 s24, v250, 36
	v_readlane_b32 s25, v250, 37
	v_mul_u32_u24_e32 v104, 0x10000, v102
	v_lshl_add_u32 v104, v103, 4, v104
	v_mul_u32_u24_e32 v105, 0x2000, v103
	v_lshl_add_u32 v105, v102, 4, v105
	s_add_u32 s22, s22, 0x800000
	s_addc_u32 s23, s23, 0
	s_add_u32 s24, s24, 0x41c0000
	s_addc_u32 s25, s25, 0
	s_mov_b32 s36, 0x2000
	s_mov_b32 s37, 0x80000
	s_movk_i32 s38, 1
	s_mov_b32 s39, 6
	s_movk_i32 s40, 64
	s_movk_i32 s41, 0x800
	s_mov_b32 s42, 0
	s_mov_b32 s43, 0
	s_movk_i32 s44, 0
	s_movk_i32 s29, 1024
	s_sub_i32 s4, s2, 0
	s_and_b32 s4, s4, 1023
	s_branch .Lsl_gu_loop
.Lsl_gu_set3:
	v_readlane_b32 s22, v250, 24
	v_readlane_b32 s23, v250, 25
	v_readlane_b32 s24, v250, 36
	v_readlane_b32 s25, v250, 37
	v_mul_u32_u24_e32 v104, 0x10000, v102
	v_lshl_add_u32 v104, v103, 4, v104
	v_mul_u32_u24_e32 v105, 0x2000, v103
	v_lshl_add_u32 v105, v102, 4, v105
	s_add_u32 s22, s22, 0x800000
	s_addc_u32 s23, s23, 0
	s_add_u32 s24, s24, 0x49c0000
	s_addc_u32 s25, s25, 0
	s_mov_b32 s36, 0x2000
	s_mov_b32 s37, 0x80000
	s_movk_i32 s38, 1
	s_mov_b32 s39, 6
	s_movk_i32 s40, 64
	s_movk_i32 s41, 0x800
	s_mov_b32 s42, 0
	s_mov_b32 s43, 0
	s_movk_i32 s44, 0
	s_movk_i32 s29, 1024
	s_sub_i32 s4, s2, 0
	s_and_b32 s4, s4, 1023
	s_branch .Lsl_gu_loop
.Lsl_gu_set4:
	v_readlane_b32 s22, v250, 26
	v_readlane_b32 s23, v250, 27
	v_readlane_b32 s24, v250, 36
	v_readlane_b32 s25, v250, 37
	v_mul_u32_u24_e32 v104, 0x10000, v102
	v_lshl_add_u32 v104, v103, 4, v104
	v_mul_u32_u24_e32 v105, 0x4000, v103
	v_lshl_add_u32 v105, v102, 4, v105
	s_add_u32 s22, s22, 0x1000000
	s_addc_u32 s23, s23, 0
	s_add_u32 s24, s24, 0x55c0000
	s_addc_u32 s25, s25, 0
	s_mov_b32 s36, 0x2000
	s_mov_b32 s37, 0x80000
	s_movk_i32 s38, 1
	s_mov_b32 s39, 6
	s_movk_i32 s40, 64
	s_movk_i32 s41, 0x1000
	s_mov_b32 s42, 0
	s_mov_b32 s43, 0
	s_movk_i32 s44, 0
	s_movk_i32 s29, 2048
	s_sub_i32 s4, s2, 0
	s_and_b32 s4, s4, 1023
	s_branch .Lsl_gu_loop
